# ssm_pre output loops: 8 bf16 per lane with ds_read_b128 and 16-byte stores instead of 2-byte elements
# speedup vs baseline: 1.0091x; 1.0091x over previous
.LBB0_373:
	s_or_b64 exec, exec, s[40:41]
	s_and_b32 s72, s65, 1
	s_add_i32 s73, s72, 1
	v_lshl_add_u32 v20, s72, 15, v0
	s_lshl_b32 s74, s73, 15
	v_cmp_gt_i32_e32 vcc, s74, v20
	s_waitcnt lgkmcnt(0)
	s_barrier
	s_and_b32 s72, s65, 1
	s_mov_b64 s[10:11], exec
	v_and_b32_e32 v56, 31, v0
	v_lshrrev_b32_e32 v57, 5, v0
	v_lshrrev_b32_e32 v58, 1, v56
	v_and_b32_e32 v59, 1, v56
	v_lshlrev_b32_e32 v59, 5, v59
	v_lshl_add_u32 v61, v57, 6, v59
	v_lshlrev_b32_e32 v60, 10, v58
	v_sub_u32_e32 v60, v61, v60
	v_mul_u32_u24_e32 v62, 0x300, v57
	v_lshl_add_u32 v62, v56, 4, v62
	s_mul_i32 s73, s36, 0x30000
	s_mul_i32 s74, s72, 0x18000
	s_add_i32 s73, s73, s74
	s_add_i32 s73, s73, 0x1000000
	s_add_u32 s40, s34, s73
	s_addc_u32 s41, s35, 0
	s_mov_b64 s[44:45], s[40:41]
	s_lshl_b32 s73, s72, 3
	s_add_i32 s74, s73, 0
	s_lshl_b32 s42, s74, 10
	v_add_u32_e32 v63, s42, v60
	v_max_i32_e32 v63, v63, v61
	ds_read_b128 v[100:103], v63 offset:25600
	ds_read_b128 v[104:107], v63 offset:25616
	s_add_i32 s74, s73, 1
	s_lshl_b32 s42, s74, 10
	v_add_u32_e32 v63, s42, v60
	v_max_i32_e32 v63, v63, v61
	ds_read_b128 v[108:111], v63 offset:25600
	ds_read_b128 v[112:115], v63 offset:25616
	s_add_i32 s74, s73, 2
	s_lshl_b32 s42, s74, 10
	v_add_u32_e32 v63, s42, v60
	v_max_i32_e32 v63, v63, v61
	ds_read_b128 v[116:119], v63 offset:25600
	ds_read_b128 v[120:123], v63 offset:25616
	s_add_i32 s74, s73, 3
	s_lshl_b32 s42, s74, 10
	v_add_u32_e32 v63, s42, v60
	v_max_i32_e32 v63, v63, v61
	ds_read_b128 v[124:127], v63 offset:25600
	ds_read_b128 v[128:131], v63 offset:25616
	s_add_i32 s74, s73, 4
	s_lshl_b32 s42, s74, 10
	v_add_u32_e32 v63, s42, v60
	v_max_i32_e32 v63, v63, v61
	ds_read_b128 v[132:135], v63 offset:25600
	ds_read_b128 v[136:139], v63 offset:25616
	s_waitcnt lgkmcnt(8)
	s_add_i32 s74, s73, 0
	v_cmp_ge_u32_e32 vcc, s74, v58
	v_cvt_pk_bf16_f32 v64, v100, v101
	v_cvt_pk_bf16_f32 v65, v102, v103
	v_cvt_pk_bf16_f32 v66, v104, v105
	v_cvt_pk_bf16_f32 v67, v106, v107
	v_cndmask_b32_e32 v64, 0, v64, vcc
	v_cndmask_b32_e32 v65, 0, v65, vcc
	v_cndmask_b32_e32 v66, 0, v66, vcc
	v_cndmask_b32_e32 v67, 0, v67, vcc
	global_store_dwordx4 v62, v[64:67], s[40:41] sc1
	s_add_u32 s40, s40, 0x3000
	s_addc_u32 s41, s41, 0
	s_add_i32 s74, s73, 5
	s_lshl_b32 s42, s74, 10
	v_add_u32_e32 v63, s42, v60
	v_max_i32_e32 v63, v63, v61
	ds_read_b128 v[140:143], v63 offset:25600
	ds_read_b128 v[144:147], v63 offset:25616
	s_waitcnt lgkmcnt(8)
	s_add_i32 s74, s73, 1
	v_cmp_ge_u32_e32 vcc, s74, v58
	v_cvt_pk_bf16_f32 v68, v108, v109
	v_cvt_pk_bf16_f32 v69, v110, v111
	v_cvt_pk_bf16_f32 v70, v112, v113
	v_cvt_pk_bf16_f32 v71, v114, v115
	v_cndmask_b32_e32 v68, 0, v68, vcc
	v_cndmask_b32_e32 v69, 0, v69, vcc
	v_cndmask_b32_e32 v70, 0, v70, vcc
	v_cndmask_b32_e32 v71, 0, v71, vcc
	global_store_dwordx4 v62, v[68:71], s[40:41] sc1
	s_add_u32 s40, s40, 0x3000
	s_addc_u32 s41, s41, 0
	s_add_i32 s74, s73, 6
	s_lshl_b32 s42, s74, 10
	v_add_u32_e32 v63, s42, v60
	v_max_i32_e32 v63, v63, v61
	ds_read_b128 v[148:151], v63 offset:25600
	ds_read_b128 v[152:155], v63 offset:25616
	s_waitcnt lgkmcnt(8)
	s_add_i32 s74, s73, 2
	v_cmp_ge_u32_e32 vcc, s74, v58
	v_cvt_pk_bf16_f32 v64, v116, v117
	v_cvt_pk_bf16_f32 v65, v118, v119
	v_cvt_pk_bf16_f32 v66, v120, v121
	v_cvt_pk_bf16_f32 v67, v122, v123
	v_cndmask_b32_e32 v64, 0, v64, vcc
	v_cndmask_b32_e32 v65, 0, v65, vcc
	v_cndmask_b32_e32 v66, 0, v66, vcc
	v_cndmask_b32_e32 v67, 0, v67, vcc
	global_store_dwordx4 v62, v[64:67], s[40:41] sc1
	s_add_u32 s40, s40, 0x3000
	s_addc_u32 s41, s41, 0
	s_add_i32 s74, s73, 7
	s_lshl_b32 s42, s74, 10
	v_add_u32_e32 v63, s42, v60
	v_max_i32_e32 v63, v63, v61
	ds_read_b128 v[156:159], v63 offset:25600
	ds_read_b128 v[160:163], v63 offset:25616
	s_waitcnt lgkmcnt(8)
	s_add_i32 s74, s73, 3
	v_cmp_ge_u32_e32 vcc, s74, v58
	v_cvt_pk_bf16_f32 v68, v124, v125
	v_cvt_pk_bf16_f32 v69, v126, v127
	v_cvt_pk_bf16_f32 v70, v128, v129
	v_cvt_pk_bf16_f32 v71, v130, v131
	v_cndmask_b32_e32 v68, 0, v68, vcc
	v_cndmask_b32_e32 v69, 0, v69, vcc
	v_cndmask_b32_e32 v70, 0, v70, vcc
	v_cndmask_b32_e32 v71, 0, v71, vcc
	global_store_dwordx4 v62, v[68:71], s[40:41] sc1
	s_add_u32 s40, s40, 0x3000
	s_addc_u32 s41, s41, 0
	s_waitcnt lgkmcnt(6)
	s_add_i32 s74, s73, 4
	v_cmp_ge_u32_e32 vcc, s74, v58
	v_cvt_pk_bf16_f32 v64, v132, v133
	v_cvt_pk_bf16_f32 v65, v134, v135
	v_cvt_pk_bf16_f32 v66, v136, v137
	v_cvt_pk_bf16_f32 v67, v138, v139
	v_cndmask_b32_e32 v64, 0, v64, vcc
	v_cndmask_b32_e32 v65, 0, v65, vcc
	v_cndmask_b32_e32 v66, 0, v66, vcc
	v_cndmask_b32_e32 v67, 0, v67, vcc
	global_store_dwordx4 v62, v[64:67], s[40:41] sc1
	s_add_u32 s40, s40, 0x3000
	s_addc_u32 s41, s41, 0
	s_waitcnt lgkmcnt(4)
	s_add_i32 s74, s73, 5
	v_cmp_ge_u32_e32 vcc, s74, v58
	v_cvt_pk_bf16_f32 v68, v140, v141
	v_cvt_pk_bf16_f32 v69, v142, v143
	v_cvt_pk_bf16_f32 v70, v144, v145
	v_cvt_pk_bf16_f32 v71, v146, v147
	v_cndmask_b32_e32 v68, 0, v68, vcc
	v_cndmask_b32_e32 v69, 0, v69, vcc
	v_cndmask_b32_e32 v70, 0, v70, vcc
	v_cndmask_b32_e32 v71, 0, v71, vcc
	global_store_dwordx4 v62, v[68:71], s[40:41] sc1
	s_add_u32 s40, s40, 0x3000
	s_addc_u32 s41, s41, 0
	s_waitcnt lgkmcnt(2)
	s_add_i32 s74, s73, 6
	v_cmp_ge_u32_e32 vcc, s74, v58
	v_cvt_pk_bf16_f32 v64, v148, v149
	v_cvt_pk_bf16_f32 v65, v150, v151
	v_cvt_pk_bf16_f32 v66, v152, v153
	v_cvt_pk_bf16_f32 v67, v154, v155
	v_cndmask_b32_e32 v64, 0, v64, vcc
	v_cndmask_b32_e32 v65, 0, v65, vcc
	v_cndmask_b32_e32 v66, 0, v66, vcc
	v_cndmask_b32_e32 v67, 0, v67, vcc
	global_store_dwordx4 v62, v[64:67], s[40:41] sc1
	s_add_u32 s40, s40, 0x3000
	s_addc_u32 s41, s41, 0
	s_waitcnt lgkmcnt(0)
	s_add_i32 s74, s73, 7
	v_cmp_ge_u32_e32 vcc, s74, v58
	v_cvt_pk_bf16_f32 v68, v156, v157
	v_cvt_pk_bf16_f32 v69, v158, v159
	v_cvt_pk_bf16_f32 v70, v160, v161
	v_cvt_pk_bf16_f32 v71, v162, v163
	v_cndmask_b32_e32 v68, 0, v68, vcc
	v_cndmask_b32_e32 v69, 0, v69, vcc
	v_cndmask_b32_e32 v70, 0, v70, vcc
	v_cndmask_b32_e32 v71, 0, v71, vcc
	global_store_dwordx4 v62, v[68:71], s[40:41] sc1
	s_add_u32 s40, s40, 0x3000
	s_addc_u32 s41, s41, 0
	v_and_b32_e32 v56, 7, v0
	v_lshrrev_b32_e32 v57, 3, v0
	v_and_b32_e32 v58, 15, v57
	v_lshlrev_b32_e32 v58, 8, v58
	v_lshl_add_u32 v58, v56, 5, v58
	v_lshrrev_b32_e32 v59, 4, v57
	v_add_u32_e32 v59, 1, v59
	v_lshlrev_b32_e32 v59, 8, v59
	v_lshl_add_u32 v59, v56, 5, v59
	s_lshl_b32 s74, s72, 11
	v_add_u32_e32 v59, s74, v59
	v_mul_u32_u24_e32 v62, 0x300, v57
	v_lshl_add_u32 v62, v56, 4, v62
	ds_read_b128 v[100:103], v58 offset:16896
	ds_read_b128 v[104:107], v58 offset:16912
	ds_read_b128 v[108:111], v58 offset:20992
	ds_read_b128 v[112:115], v58 offset:21008
	ds_read_b128 v[116:119], v59 offset:0
	ds_read_b128 v[120:123], v59 offset:16
	ds_read_b128 v[124:127], v59 offset:4352
	ds_read_b128 v[128:131], v59 offset:4368
	ds_read_b128 v[132:135], v58 offset:16896
	ds_read_b128 v[136:139], v58 offset:16912
	ds_read_b128 v[140:143], v58 offset:20992
	ds_read_b128 v[144:147], v58 offset:21008
	ds_read_b128 v[148:151], v59 offset:1024
	ds_read_b128 v[152:155], v59 offset:1040
	s_waitcnt lgkmcnt(6)
	ds_read_b128 v[156:159], v59 offset:5376
	ds_read_b128 v[160:163], v59 offset:5392
	v_mul_f32_e32 v72, v108, v124
	v_mul_f32_e32 v80, v100, v124
	v_mul_f32_e32 v73, v109, v125
	v_mul_f32_e32 v81, v101, v125
	v_mul_f32_e32 v74, v110, v126
	v_mul_f32_e32 v82, v102, v126
	v_mul_f32_e32 v75, v111, v127
	v_mul_f32_e32 v83, v103, v127
	v_mul_f32_e32 v76, v112, v128
	v_mul_f32_e32 v84, v104, v128
	v_mul_f32_e32 v77, v113, v129
	v_mul_f32_e32 v85, v105, v129
	v_mul_f32_e32 v78, v114, v130
	v_mul_f32_e32 v86, v106, v130
	v_mul_f32_e32 v79, v115, v131
	v_mul_f32_e32 v87, v107, v131
	v_fma_f32 v72, v100, v116, -v72
	v_fmac_f32_e32 v80, v108, v116
	v_fma_f32 v73, v101, v117, -v73
	v_fmac_f32_e32 v81, v109, v117
	v_fma_f32 v74, v102, v118, -v74
	v_fmac_f32_e32 v82, v110, v118
	v_fma_f32 v75, v103, v119, -v75
	v_fmac_f32_e32 v83, v111, v119
	v_fma_f32 v76, v104, v120, -v76
	v_fmac_f32_e32 v84, v112, v120
	v_fma_f32 v77, v105, v121, -v77
	v_fmac_f32_e32 v85, v113, v121
	v_fma_f32 v78, v106, v122, -v78
	v_fmac_f32_e32 v86, v114, v122
	v_fma_f32 v79, v107, v123, -v79
	v_fmac_f32_e32 v87, v115, v123
	v_cvt_pk_bf16_f32 v64, v72, v73
	v_cvt_pk_bf16_f32 v68, -v80, -v81
	v_cvt_pk_bf16_f32 v65, v74, v75
	v_cvt_pk_bf16_f32 v69, -v82, -v83
	v_cvt_pk_bf16_f32 v66, v76, v77
	v_cvt_pk_bf16_f32 v70, -v84, -v85
	v_cvt_pk_bf16_f32 v67, v78, v79
	v_cvt_pk_bf16_f32 v71, -v86, -v87
	global_store_dwordx4 v62, v[64:67], s[44:45] offset:512 sc1
	global_store_dwordx4 v62, v[68:71], s[44:45] offset:640 sc1
	s_add_u32 s44, s44, 0xc000
	s_addc_u32 s45, s45, 0
	s_waitcnt lgkmcnt(0)
	s_nop 0
	v_mul_f32_e32 v72, v140, v156
	v_mul_f32_e32 v80, v132, v156
	v_mul_f32_e32 v73, v141, v157
	v_mul_f32_e32 v81, v133, v157
	v_mul_f32_e32 v74, v142, v158
	v_mul_f32_e32 v82, v134, v158
	v_mul_f32_e32 v75, v143, v159
	v_mul_f32_e32 v83, v135, v159
	v_mul_f32_e32 v76, v144, v160
	v_mul_f32_e32 v84, v136, v160
	v_mul_f32_e32 v77, v145, v161
	v_mul_f32_e32 v85, v137, v161
	v_mul_f32_e32 v78, v146, v162
	v_mul_f32_e32 v86, v138, v162
	v_mul_f32_e32 v79, v147, v163
	v_mul_f32_e32 v87, v139, v163
	v_fma_f32 v72, v132, v148, -v72
	v_fmac_f32_e32 v80, v140, v148
	v_fma_f32 v73, v133, v149, -v73
	v_fmac_f32_e32 v81, v141, v149
	v_fma_f32 v74, v134, v150, -v74
	v_fmac_f32_e32 v82, v142, v150
	v_fma_f32 v75, v135, v151, -v75
	v_fmac_f32_e32 v83, v143, v151
	v_fma_f32 v76, v136, v152, -v76
	v_fmac_f32_e32 v84, v144, v152
	v_fma_f32 v77, v137, v153, -v77
	v_fmac_f32_e32 v85, v145, v153
	v_fma_f32 v78, v138, v154, -v78
	v_fmac_f32_e32 v86, v146, v154
	v_fma_f32 v79, v139, v155, -v79
	v_fmac_f32_e32 v87, v147, v155
	v_cvt_pk_bf16_f32 v64, v72, v73
	v_cvt_pk_bf16_f32 v68, -v80, -v81
	v_cvt_pk_bf16_f32 v65, v74, v75
	v_cvt_pk_bf16_f32 v69, -v82, -v83
	v_cvt_pk_bf16_f32 v66, v76, v77
	v_cvt_pk_bf16_f32 v70, -v84, -v85
	v_cvt_pk_bf16_f32 v67, v78, v79
	v_cvt_pk_bf16_f32 v71, -v86, -v87
	global_store_dwordx4 v62, v[64:67], s[44:45] offset:512 sc1
	global_store_dwordx4 v62, v[68:71], s[44:45] offset:640 sc1
	v_and_b32_e32 v56, 31, v0
	v_lshrrev_b32_e32 v57, 5, v0
	v_lshrrev_b32_e32 v58, 1, v56
	v_sub_u32_e32 v58, 15, v58
	v_lshlrev_b32_e32 v58, 8, v58
	v_lshl_add_u32 v58, v57, 2, v58
	s_lshl_b32 s74, s72, 7
	v_add_u32_e32 v58, s74, v58
	v_and_b32_e32 v59, 1, v56
	v_lshlrev_b32_e32 v59, 5, v59
	v_lshl_add_u32 v59, v57, 6, v59
	s_lshl_b32 s74, s72, 11
	v_add_u32_e32 v59, s74, v59
	v_lshlrev_b32_e32 v62, 9, v57
	v_lshl_add_u32 v62, v56, 4, v62
	s_lshl_b32 s73, s36, 16
	s_lshl_b32 s74, s72, 14
	s_add_i32 s73, s73, s74
	s_add_i32 s73, s73, 0x800000
	s_add_u32 s40, s34, s73
	s_addc_u32 s41, s35, 0
	s_add_u32 s42, s40, 0x8000
	s_addc_u32 s43, s41, 0
	ds_read_b32 v116, v58
	ds_read_b32 v117, v58 offset:4352
	ds_read_b128 v[100:103], v59 offset:8704
	ds_read_b128 v[104:107], v59 offset:8720
	ds_read_b128 v[108:111], v59 offset:12800
	ds_read_b128 v[112:115], v59 offset:12816
	ds_read_b32 v148, v58 offset:64
	ds_read_b32 v149, v58 offset:4416
	ds_read_b128 v[132:135], v59 offset:9728
	ds_read_b128 v[136:139], v59 offset:9744
	ds_read_b128 v[140:143], v59 offset:13824
	ds_read_b128 v[144:147], v59 offset:13840
	s_waitcnt lgkmcnt(6)
	v_mul_f32_e32 v72, v117, v108
	v_mul_f32_e32 v80, v116, v108
	v_mul_f32_e32 v73, v117, v109
	v_mul_f32_e32 v81, v116, v109
	v_mul_f32_e32 v74, v117, v110
	v_mul_f32_e32 v82, v116, v110
	v_mul_f32_e32 v75, v117, v111
	v_mul_f32_e32 v83, v116, v111
	v_mul_f32_e32 v76, v117, v112
	v_mul_f32_e32 v84, v116, v112
	v_mul_f32_e32 v77, v117, v113
	v_mul_f32_e32 v85, v116, v113
	v_mul_f32_e32 v78, v117, v114
	v_mul_f32_e32 v86, v116, v114
	v_mul_f32_e32 v79, v117, v115
	v_mul_f32_e32 v87, v116, v115
	v_fma_f32 v72, v116, v100, -v72
	v_fmac_f32_e32 v80, v117, v100
	v_fma_f32 v73, v116, v101, -v73
	v_fmac_f32_e32 v81, v117, v101
	v_fma_f32 v74, v116, v102, -v74
	v_fmac_f32_e32 v82, v117, v102
	v_fma_f32 v75, v116, v103, -v75
	v_fmac_f32_e32 v83, v117, v103
	v_fma_f32 v76, v116, v104, -v76
	v_fmac_f32_e32 v84, v117, v104
	v_fma_f32 v77, v116, v105, -v77
	v_fmac_f32_e32 v85, v117, v105
	v_fma_f32 v78, v116, v106, -v78
	v_fmac_f32_e32 v86, v117, v106
	v_fma_f32 v79, v116, v107, -v79
	v_fmac_f32_e32 v87, v117, v107
	v_cvt_pk_bf16_f32 v64, v72, v73
	v_cvt_pk_bf16_f32 v68, v80, v81
	v_cvt_pk_bf16_f32 v65, v74, v75
	v_cvt_pk_bf16_f32 v69, v82, v83
	v_cvt_pk_bf16_f32 v66, v76, v77
	v_cvt_pk_bf16_f32 v70, v84, v85
	v_cvt_pk_bf16_f32 v67, v78, v79
	v_cvt_pk_bf16_f32 v71, v86, v87
	global_store_dwordx4 v62, v[64:67], s[40:41] sc1
	global_store_dwordx4 v62, v[68:71], s[42:43] sc1
	s_nop 1
	s_waitcnt lgkmcnt(0)
	v_mul_f32_e32 v72, v149, v140
	v_mul_f32_e32 v80, v148, v140
	v_mul_f32_e32 v73, v149, v141
	v_mul_f32_e32 v81, v148, v141
	v_mul_f32_e32 v74, v149, v142
	v_mul_f32_e32 v82, v148, v142
	v_mul_f32_e32 v75, v149, v143
	v_mul_f32_e32 v83, v148, v143
	v_mul_f32_e32 v76, v149, v144
	v_mul_f32_e32 v84, v148, v144
	v_mul_f32_e32 v77, v149, v145
	v_mul_f32_e32 v85, v148, v145
	v_mul_f32_e32 v78, v149, v146
	v_mul_f32_e32 v86, v148, v146
	v_mul_f32_e32 v79, v149, v147
	v_mul_f32_e32 v87, v148, v147
	v_fma_f32 v72, v148, v132, -v72
	v_fmac_f32_e32 v80, v149, v132
	v_fma_f32 v73, v148, v133, -v73
	v_fmac_f32_e32 v81, v149, v133
	v_fma_f32 v74, v148, v134, -v74
	v_fmac_f32_e32 v82, v149, v134
	v_fma_f32 v75, v148, v135, -v75
	v_fmac_f32_e32 v83, v149, v135
	v_fma_f32 v76, v148, v136, -v76
	v_fmac_f32_e32 v84, v149, v136
	v_fma_f32 v77, v148, v137, -v77
	v_fmac_f32_e32 v85, v149, v137
	v_fma_f32 v78, v148, v138, -v78
	v_fmac_f32_e32 v86, v149, v138
	v_fma_f32 v79, v148, v139, -v79
	v_fmac_f32_e32 v87, v149, v139
	v_cvt_pk_bf16_f32 v64, v72, v73
	v_cvt_pk_bf16_f32 v68, v80, v81
	v_cvt_pk_bf16_f32 v65, v74, v75
	v_cvt_pk_bf16_f32 v69, v82, v83
	v_cvt_pk_bf16_f32 v66, v76, v77
	v_cvt_pk_bf16_f32 v70, v84, v85
	v_cvt_pk_bf16_f32 v67, v78, v79
	v_cvt_pk_bf16_f32 v71, v86, v87
	s_add_u32 s40, s40, 0x2000
	s_addc_u32 s41, s41, 0
	s_add_u32 s42, s42, 0x2000
	s_addc_u32 s43, s43, 0
	global_store_dwordx4 v62, v[64:67], s[40:41] sc1
	global_store_dwordx4 v62, v[68:71], s[42:43] sc1
